# retention: chunk loop unrolled x2 with two alternating global-load register sets (no per-chunk copy, counted vmcnt), 2 barriers per chunk
# baseline (speedup 1.0000x reference)
; #define LAS __attribute__((address_space(3)))
; __device__ __forceinline__ void ret_mfma(const Params& P, LAS unsigned char* lds, int wave) {
;     ...
;         const float gam = 1.f - exp2f(-5.f - (float)hh), lg = log2f(gam), g64 = exp2f(lg * 64.f);
;         for (int i = t; i < 33792 / 16; i += NTHREADS) *(LAS u32x4*)(lds + ST_OFF + i * 16) = (u32x4){0u, 0u, 0u, 0u};
;         f32x16 st[2];
; #pragma unroll
;         for (int a = 0; a < 2; ++a)
; #pragma unroll
;             for (int i = 0; i < 16; ++i) st[a][i] = 0.f;
;         const size_t rb = (size_t)b * SEQ;
;         float dec[16];
;         { const int mblk = (wave & 3) >> 1, nblk = wave & 1, n = nblk * 32 + q32;
; #pragma unroll
;           for (int i = 0; i < 16; ++i) { const int mm = mblk * 32 + 8 * (i >> 2) + 4 * hf + (i & 3); const int dist = n > mm ? n - mm : mm - n;
;               dec[i] = wave < 4 ? __builtin_amdgcn_exp2f(lg * (float)(dist - (63 - mm))) : __builtin_amdgcn_exp2f(lg * (float)(n + 1)); } }
;         u32x4 pq[4], pkk[4], pvv;
;         const int vr = t >> 3, vc = t & 7;
; #pragma unroll
;         for (int i = 0; i < 4; ++i) { const int id = t + 512 * i, r = id >> 5, ch = id & 31;
;             pq[i] = *(const u32x4*)(QK + (rb + r) * 2048 + hh * 256 + ch * 8); pkk[i] = *(const u32x4*)(QK + (rb + r) * 2048 + 1024 + hh * 256 + ch * 8); }
.LBB0_252:
	s_or_b64 exec, exec, s[8:9]
	s_ashr_i32 s9, s28, 6
	s_and_b32 s23, s9, 3
	v_cvt_f32_ubyte0_e32 v0, s23
	v_sub_f32_e32 v0, 0xc0a00000, v0
	v_cmp_gt_f32_e32 vcc, s25, v0
	s_lshl_b32 s8, s28, 2
	s_and_b32 s8, s8, 28
	v_cndmask_b32_e32 v1, 0, v182, vcc
	v_add_f32_e32 v0, v0, v1
	s_add_i32 s8, s8, s9
	v_exp_f32_e32 v0, v0
	s_bfe_u32 s22, s28, 0x30003
	s_ashr_i32 s8, s8, 2
	s_and_b64 s[18:19], vcc, exec
	s_cselect_b32 s9, 0xffffffc0, 0
	v_ldexp_f32 v0, v0, s9
	v_sub_f32_e32 v0, 1.0, v0
	v_cmp_gt_f32_e32 vcc, s26, v0
	s_and_b64 s[18:19], vcc, exec
	s_cselect_b32 s9, 32, 0
	v_ldexp_f32 v0, v0, s9
	v_log_f32_e32 v2, v0
	v_cndmask_b32_e32 v1, 0, v183, vcc
	s_mov_b32 s21, s15
	v_mov_b32_e32 v103, v91
	v_sub_f32_e32 v1, v2, v1
	v_mul_f32_e32 v2, 0x42800000, v1
	v_cmp_gt_f32_e32 vcc, s25, v2
	s_and_b64 s[18:19], vcc, exec
	s_cselect_b32 s9, 0xffffffc0, 0
	v_cndmask_b32_e32 v2, 0, v182, vcc
	v_fmac_f32_e32 v2, 0x42800000, v1
	v_exp_f32_e32 v2, v2
	v_mul_f32_e32 v3, v1, v85
	v_mul_f32_e32 v4, v1, v152
	v_exp_f32_e32 v3, v3
	v_ldexp_f32 v106, v2, s9
	v_mul_f32_e32 v2, v1, v153
	v_exp_f32_e32 v105, v2
	v_mul_f32_e32 v2, v1, v154
	v_exp_f32_e32 v110, v2
	v_mul_f32_e32 v2, v1, v155
	v_exp_f32_e32 v111, v2
	v_mul_f32_e32 v2, v1, v156
	v_exp_f32_e32 v104, v4
	v_exp_f32_e32 v112, v2
	v_mul_f32_e32 v2, v1, v157
	v_exp_f32_e32 v113, v2
	v_mul_f32_e32 v2, v1, v158
	s_ashr_i32 s9, s8, 31
	v_exp_f32_e32 v114, v2
	v_mul_f32_e32 v2, v1, v159
	v_exp_f32_e32 v115, v2
	v_mul_f32_e32 v2, v1, v160
	s_lshl_b64 s[18:19], s[8:9], 12
	v_cndmask_b32_e64 v108, v3, v104, s[4:5]
	v_exp_f32_e32 v116, v2
	v_lshl_add_u64 v[2:3], s[18:19], 0, v[92:93]
	v_lshlrev_b64 v[2:3], 12, v[2:3]
	v_lshl_add_u64 v[2:3], s[44:45], 0, v[2:3]
	s_lshl_b32 s14, s23, 9
	v_lshl_add_u64 v[2:3], v[2:3], 0, s[14:15]
	v_lshl_add_u64 v[2:3], v[2:3], 0, v[90:91]
	s_waitcnt vmcnt(0)
; #define LAS __attribute__((address_space(3)))
; __device__ __forceinline__ void ret_mfma(const Params& P, LAS unsigned char* lds, int wave) {
;     ...
;         for (int i = 0; i < 4; ++i) { const int id = t + 512 * i, r = id >> 5, ch = id & 31;
;             pq[i] = *(const u32x4*)(QK + (rb + r) * 2048 + hh * 256 + ch * 8); pkk[i] = *(const u32x4*)(QK + (rb + r) * 2048 + 1024 + hh * 256 + ch * 8); }
;         pvv = *(const u32x4*)(V + (rb + vr) * 2048 + hh * 512 + slice * 64 + vc * 8);
; #pragma unroll 1
;         for (int c = 0; c < 64; ++c) {
; #pragma unroll
;             for (int i = 0; i < 4; ++i) { const int id = t + 512 * i, r = id >> 5, ch = id & 31;
;                 *(LAS u32x4*)(lds + Q_OFF + r * QP + ch * 16) = pq[i]; *(LAS u32x4*)(lds + K_OFF + r * QP + ch * 16) = pkk[i]; }
;             *(LAS u32x4*)(lds + V_OFF + vr * VP + vc * 16) = pvv;
;             __syncthreads();
;             if (c + 1 < 64) { const size_t r1 = rb + (size_t)(c + 1) * 64;
; #pragma unroll
;                 for (int i = 0; i < 4; ++i) { const int id = t + 512 * i, r = id >> 5, ch = id & 31;
;                     pq[i] = *(const u32x4*)(QK + (r1 + r) * 2048 + hh * 256 + ch * 8); pkk[i] = *(const u32x4*)(QK + (r1 + r) * 2048 + 1024 + hh * 256 + ch * 8); }
;                 pvv = *(const u32x4*)(V + (r1 + vr) * 2048 + hh * 512 + slice * 64 + vc * 8); }
	flat_load_dwordx4 v[48:51], v[2:3]
	flat_load_dwordx4 v[52:55], v[2:3] offset:2048
	v_lshl_add_u64 v[2:3], s[18:19], 0, v[94:95]
	v_lshlrev_b64 v[2:3], 12, v[2:3]
	v_lshl_add_u64 v[2:3], s[44:45], 0, v[2:3]
	v_lshl_add_u64 v[2:3], v[2:3], 0, s[14:15]
	v_lshl_add_u64 v[2:3], v[2:3], 0, v[90:91]
	flat_load_dwordx4 v[56:59], v[2:3]
	flat_load_dwordx4 v[60:63], v[2:3] offset:2048
	v_lshl_add_u64 v[2:3], s[18:19], 0, v[96:97]
	v_lshlrev_b64 v[2:3], 12, v[2:3]
	v_lshl_add_u64 v[2:3], s[44:45], 0, v[2:3]
	v_lshl_add_u64 v[2:3], v[2:3], 0, s[14:15]
	v_lshl_add_u64 v[2:3], v[2:3], 0, v[90:91]
	flat_load_dwordx4 v[64:67], v[2:3]
	flat_load_dwordx4 v[68:71], v[2:3] offset:2048
	v_lshl_add_u64 v[2:3], s[18:19], 0, v[98:99]
	v_lshlrev_b64 v[2:3], 12, v[2:3]
	v_lshl_add_u64 v[2:3], s[44:45], 0, v[2:3]
	v_lshl_add_u64 v[2:3], v[2:3], 0, s[14:15]
	v_lshl_add_u64 v[2:3], v[2:3], 0, v[90:91]
	flat_load_dwordx4 v[72:75], v[2:3]
	flat_load_dwordx4 v[76:79], v[2:3] offset:2048
	v_lshl_add_u64 v[2:3], s[18:19], 0, v[88:89]
	v_lshlrev_b64 v[2:3], 12, v[2:3]
	v_lshl_add_u64 v[2:3], s[36:37], 0, v[2:3]
	s_lshl_b32 s8, s23, 10
	s_mov_b32 s9, s15
	v_lshl_add_u64 v[2:3], v[2:3], 0, s[8:9]
	s_lshl_b32 s20, s22, 7
	v_lshl_add_u64 v[2:3], v[2:3], 0, s[20:21]
	v_lshl_add_u64 v[2:3], v[2:3], 0, v[102:103]
	flat_load_dwordx4 v[80:83], v[2:3]
	s_add_u32 s8, s36, s8
	s_addc_u32 s9, s37, 0
	s_add_u32 s8, s8, s20
	v_mul_f32_e32 v2, v1, v161
	s_addc_u32 s9, s9, 0
	s_lshl_b32 s20, s23, 6
	v_exp_f32_e32 v117, v2
	v_mul_f32_e32 v2, v1, v162
	s_add_u32 s20, s60, s20
	v_exp_f32_e32 v118, v2
	v_mul_f32_e32 v2, v1, v163
	s_addc_u32 s21, s61, 0
	s_lshl_b32 s22, s22, 3
	v_exp_f32_e32 v119, v2
	v_mul_f32_e32 v2, v1, v164
	s_add_u32 s20, s20, s22
	v_exp_f32_e32 v120, v2
	v_mul_f32_e32 v2, v1, v165
	s_addc_u32 s21, s21, 0
	v_exp_f32_e32 v121, v2
	v_mul_f32_e32 v2, v1, v166
	v_mul_f32_e32 v1, v1, v167
	s_add_u32 s20, s20, s16
	v_exp_f32_e32 v122, v2
	v_exp_f32_e32 v123, v1
	s_addc_u32 s21, s21, s17
	v_lshl_add_u64 v[124:125], s[8:9], 0, v[102:103]
	s_add_u32 s8, s8, s27
	v_mov_b32_e32 v0, 0
	s_addc_u32 s9, s9, 0
	s_mov_b32 s29, 0
	v_mov_b32_e32 v126, v106
	v_mov_b32_e32 v127, v106
	v_lshl_add_u64 v[128:129], v[86:87], 1, s[8:9]
	v_mov_b32_e32 v109, v108
	v_lshl_add_u64 v[144:145], v[100:101], 0, s[14:15]
	v_mov_b32_e32 v1, v0
	v_mov_b32_e32 v2, v0
	v_mov_b32_e32 v3, v0
	v_mov_b32_e32 v4, v0
	v_mov_b32_e32 v5, v0
	v_mov_b32_e32 v6, v0
	v_mov_b32_e32 v7, v0
	v_mov_b32_e32 v8, v0
	v_mov_b32_e32 v9, v0
	v_mov_b32_e32 v10, v0
	v_mov_b32_e32 v11, v0
	v_mov_b32_e32 v12, v0
	v_mov_b32_e32 v13, v0
	v_mov_b32_e32 v14, v0
	v_mov_b32_e32 v15, v0
	v_mov_b32_e32 v16, v0
	v_mov_b32_e32 v17, v0
	v_mov_b32_e32 v18, v0
	v_mov_b32_e32 v19, v0
	v_mov_b32_e32 v20, v0
	v_mov_b32_e32 v21, v0
	v_mov_b32_e32 v22, v0
	v_mov_b32_e32 v23, v0
	v_mov_b32_e32 v24, v0
	v_mov_b32_e32 v25, v0
	v_mov_b32_e32 v26, v0
	v_mov_b32_e32 v27, v0
	v_mov_b32_e32 v28, v0
	v_mov_b32_e32 v29, v0
	v_mov_b32_e32 v30, v0
	v_mov_b32_e32 v31, v0
	s_add_u32 s8, s18, 64
	s_addc_u32 s9, s19, 0
	v_lshl_add_u64 v[32:33], s[8:9], 0, v[92:93]
	v_lshlrev_b64 v[32:33], 12, v[32:33]
	v_lshl_add_u64 v[32:33], v[144:145], 0, v[32:33]
	global_load_dwordx4 v[226:229], v[32:33], off
	global_load_dwordx4 v[230:233], v[32:33], off offset:2048
	v_lshl_add_u64 v[32:33], s[8:9], 0, v[94:95]
	v_lshlrev_b64 v[32:33], 12, v[32:33]
	v_lshl_add_u64 v[32:33], v[144:145], 0, v[32:33]
	global_load_dwordx4 v[234:237], v[32:33], off
	global_load_dwordx4 v[238:241], v[32:33], off offset:2048
	v_lshl_add_u64 v[32:33], s[8:9], 0, v[96:97]
	v_lshlrev_b64 v[32:33], 12, v[32:33]
	v_lshl_add_u64 v[32:33], v[144:145], 0, v[32:33]
	global_load_dwordx4 v[246:249], v[32:33], off
	global_load_dwordx4 v[250:253], v[32:33], off offset:2048
	v_lshl_add_u64 v[32:33], s[8:9], 0, v[98:99]
	v_lshlrev_b64 v[32:33], 12, v[32:33]
	v_lshl_add_u64 v[32:33], v[144:145], 0, v[32:33]
	global_load_dwordx4 v[206:209], v[32:33], off
	global_load_dwordx4 v[130:133], v[32:33], off offset:2048
	v_lshl_add_u64 v[32:33], s[8:9], 0, v[88:89]
	v_lshlrev_b64 v[32:33], 12, v[32:33]
	v_lshl_add_u64 v[32:33], v[124:125], 0, v[32:33]
	global_load_dwordx4 v[134:137], v[32:33], off
	s_waitcnt vmcnt(0)
	ds_write_b128 v173, v[48:51]
	ds_write_b128 v173, v[52:55] offset:33792
	ds_write_b128 v174, v[56:59]
	ds_write_b128 v174, v[60:63] offset:33792
	ds_write_b128 v175, v[64:67]
	ds_write_b128 v175, v[68:71] offset:33792
	ds_write_b128 v176, v[72:75]
	ds_write_b128 v176, v[76:79] offset:33792
	ds_write_b128 v177, v[80:83]
	s_waitcnt lgkmcnt(0)
	s_add_u32 s8, s18, 0x80
	s_addc_u32 s9, s19, 0
	v_lshl_add_u64 v[32:33], s[8:9], 0, v[92:93]
	v_lshlrev_b64 v[32:33], 12, v[32:33]
	v_lshl_add_u64 v[32:33], v[144:145], 0, v[32:33]
	global_load_dwordx4 v[48:51], v[32:33], off
	global_load_dwordx4 v[52:55], v[32:33], off offset:2048
	v_lshl_add_u64 v[32:33], s[8:9], 0, v[94:95]
	v_lshlrev_b64 v[32:33], 12, v[32:33]
	v_lshl_add_u64 v[32:33], v[144:145], 0, v[32:33]
	global_load_dwordx4 v[56:59], v[32:33], off
	global_load_dwordx4 v[60:63], v[32:33], off offset:2048
	v_lshl_add_u64 v[32:33], s[8:9], 0, v[96:97]
	v_lshlrev_b64 v[32:33], 12, v[32:33]
	v_lshl_add_u64 v[32:33], v[144:145], 0, v[32:33]
	global_load_dwordx4 v[64:67], v[32:33], off
	global_load_dwordx4 v[68:71], v[32:33], off offset:2048
	v_lshl_add_u64 v[32:33], s[8:9], 0, v[98:99]
	v_lshlrev_b64 v[32:33], 12, v[32:33]
	v_lshl_add_u64 v[32:33], v[144:145], 0, v[32:33]
	global_load_dwordx4 v[72:75], v[32:33], off
	global_load_dwordx4 v[76:79], v[32:33], off offset:2048
	v_lshl_add_u64 v[32:33], s[8:9], 0, v[88:89]
	v_lshlrev_b64 v[32:33], 12, v[32:33]
	v_lshl_add_u64 v[32:33], v[124:125], 0, v[32:33]
	global_load_dwordx4 v[80:83], v[32:33], off
	s_mov_b32 s30, 0
	s_barrier
	s_branch .Lret_even

; __device__ __forceinline__ void ret_mfma(const Params& P, LAS unsigned char* lds, int wave) {
;     ...
;             __syncthreads();
;             if (c + 1 < 64) { const size_t r1 = rb + (size_t)(c + 1) * 64;
; #pragma unroll
;                 for (int i = 0; i < 4; ++i) { const int id = t + 512 * i, r = id >> 5, ch = id & 31;
;                     pq[i] = *(const u32x4*)(QK + (r1 + r) * 2048 + hh * 256 + ch * 8); pkk[i] = *(const u32x4*)(QK + (r1 + r) * 2048 + 1024 + hh * 256 + ch * 8); }
;                 pvv = *(const u32x4*)(V + (r1 + vr) * 2048 + hh * 512 + slice * 64 + vc * 8); }
.Lret_b_e:
	s_waitcnt lgkmcnt(0)
	s_barrier
	s_cmp_lt_u32 s29, 62
	s_cbranch_scc0 .Lret_wtail_e
	s_andn2_b64 vcc, exec, s[10:11]
	s_cbranch_vccnz .Lret_w9_e
	s_waitcnt vmcnt(14)
	s_branch .Lret_wd_e
.Lret_w9_e:
	s_waitcnt vmcnt(9)
	s_branch .Lret_wd_e
.Lret_wtail_e:
	s_andn2_b64 vcc, exec, s[10:11]
	s_cbranch_vccnz .Lret_w0_e
	s_waitcnt vmcnt(5)
	s_branch .Lret_wd_e

; #define LAS __attribute__((address_space(3)))
; __device__ __forceinline__ unsigned cvt_pk_bf16(float lo, float hi) { f32x2 v = {lo, hi}; bf16x2_t b = __builtin_convertvector(v, bf16x2_t); return __builtin_bit_cast(unsigned, b); }
; __device__ __forceinline__ void ret_mfma(const Params& P, LAS unsigned char* lds, int wave) {
;     ...
;             for (int i = 0; i < 4; ++i) { const int id = t + 512 * i, r = id >> 5, ch = id & 31;
;                 *(LAS u32x4*)(lds + Q_OFF + r * QP + ch * 16) = pq[i]; *(LAS u32x4*)(lds + K_OFF + r * QP + ch * 16) = pkk[i]; }
;             *(LAS u32x4*)(lds + V_OFF + vr * VP + vc * 16) = pvv;
;     ...
; #pragma unroll
;                 for (int vb = 0; vb < 2; ++vb)
; #pragma unroll
;                     for (int i = 0; i < 16; ++i) { const int dv = vb * 32 + 8 * (i >> 2) + 4 * hf + (i & 3);
;                         *(LAS bf16_t*)(lds + ST_OFF + dv * QP + (wave * 32 + q32) * 2) = (bf16_t)(cvt_pk_bf16(st[vb][i], 0.f) & 0xffffu); }
;             }
;             if (wave >= 4) {
;                 const int w4 = wave - 4, dvblk = w4 >> 1, nblk = w4 & 1, n = nblk * 32 + q32;
; #pragma unroll
;                 for (int ks = 0; ks < 4; ++ks) {
;                     const LAS unsigned char* p = lds + V_OFF + (16 * ks + trrow) * VP + dvblk * 64 + trcol;
;                     const bf16x8 a = tr_pair(p, p + 4 * VP);
;                     const bf16x8 bs = *(const LAS bf16x8*)(lds + S_OFF + n * SP + (16 * ks + 8 * hf) * 2);
;                     acc = __builtin_amdgcn_mfma_f32_32x32x16_bf16(a, bs, acc, 0, 0, 0);
;                 }
;                 float sq = 0.f;
; #pragma unroll
;                 for (int i = 0; i < 16; ++i) sq += acc[i] * acc[i];
;                 sq += __shfl_xor(sq, 32);
;                 if (hf == 0) rssq[(r0 + n) * 64 + hh * 16 + slice * 2 + dvblk] = sq;
;                 bf16_t* op = V + (r0 + n) * 2048 + hh * 512 + slice * 64 + dvblk * 32 + 4 * hf;
; #pragma unroll
;                 for (int j = 0; j < 4; ++j) { u32x2 w; w.x = cvt_pk_bf16(acc[4 * j], acc[4 * j + 1]); w.y = cvt_pk_bf16(acc[4 * j + 2], acc[4 * j + 3]); *(u32x2*)(op + 8 * j) = w; }
;             }
.Lret_wd_e:
	s_xor_b32 s31, s30, 0x3000
	v_add_u32_e32 v107, s31, v177
	ds_write_b128 v173, v[226:229]
	ds_write_b128 v173, v[230:233] offset:33792
	ds_write_b128 v174, v[234:237]
	ds_write_b128 v174, v[238:241] offset:33792
	ds_write_b128 v175, v[246:249]
	ds_write_b128 v175, v[250:253] offset:33792
	ds_write_b128 v176, v[206:209]
	ds_write_b128 v176, v[130:133] offset:33792
	ds_write_b128 v107, v[134:137]
	s_and_b64 vcc, exec, s[8:9]
	v_cvt_pk_bf16_f32 v218, v0, v1
	v_cvt_pk_bf16_f32 v219, v2, v3
	ds_write_b64 v242, v[218:219]
	v_cvt_pk_bf16_f32 v220, v4, v5
	v_cvt_pk_bf16_f32 v221, v6, v7
	ds_write_b64 v242, v[220:221] offset:16
	v_cvt_pk_bf16_f32 v222, v8, v9
	v_cvt_pk_bf16_f32 v223, v10, v11
	ds_write_b64 v242, v[222:223] offset:32
	v_cvt_pk_bf16_f32 v224, v12, v13
	v_cvt_pk_bf16_f32 v225, v14, v15
	ds_write_b64 v242, v[224:225] offset:48
	v_cvt_pk_bf16_f32 v218, v16, v17
	v_cvt_pk_bf16_f32 v219, v18, v19
	ds_write_b64 v242, v[218:219] offset:16896
	v_cvt_pk_bf16_f32 v220, v20, v21
	v_cvt_pk_bf16_f32 v221, v22, v23
	ds_write_b64 v242, v[220:221] offset:16912
	v_cvt_pk_bf16_f32 v222, v24, v25
	v_cvt_pk_bf16_f32 v223, v26, v27
	ds_write_b64 v242, v[222:223] offset:16928
	v_cvt_pk_bf16_f32 v224, v28, v29
	v_cvt_pk_bf16_f32 v225, v30, v31
	ds_write_b64 v242, v[224:225] offset:16944
	s_cbranch_vccnz .Lret_s4_e
	v_add_u32_e32 v185, s30, v181
	ds_read_b64_tr_b16 v[190:191], v185
	ds_read_b64_tr_b16 v[192:193], v185 offset:768
	v_add_u32_e32 v103, v151, v149
	ds_read_b128 v[194:197], v103
	ds_read_b64_tr_b16 v[198:199], v185 offset:3072
	ds_read_b64_tr_b16 v[200:201], v185 offset:3840
	ds_read_b128 v[202:205], v103 offset:32
	v_and_b32_e32 v107, 64, v184
	v_add_u32_e32 v107, 64, v107
	s_waitcnt lgkmcnt(0)
	v_mfma_f32_32x32x16_bf16 v[32:47], v[190:193], v[194:197], v[32:47]
	s_lshl_b32 s8, s29, 6
	s_or_b32 s8, s18, s8
	v_or_b32_e32 v146, s8, v84
	v_mfma_f32_32x32x16_bf16 v[32:47], v[198:201], v[202:205], v[32:47]
	ds_read_b64_tr_b16 v[190:191], v185 offset:6144
	ds_read_b64_tr_b16 v[192:193], v185 offset:6912
	ds_read_b128 v[194:197], v103 offset:64
	ds_read_b64_tr_b16 v[198:199], v185 offset:9216
	ds_read_b64_tr_b16 v[200:201], v185 offset:9984
	ds_read_b128 v[202:205], v103 offset:96
	v_xor_b32_e32 v103, 32, v184
	v_cmp_lt_i32_e32 vcc, v103, v107
	s_nop 1
	v_cndmask_b32_e32 v107, v184, v103, vcc
	v_lshlrev_b32_e32 v107, 2, v107
	s_waitcnt lgkmcnt(0)
	v_mfma_f32_32x32x16_bf16 v[32:47], v[190:193], v[194:197], v[32:47]
	v_mfma_f32_32x32x16_bf16 v[32:47], v[198:201], v[202:205], v[32:47]
	s_nop 11
	v_mul_f32_e32 v103, v33, v33
	v_fmac_f32_e32 v103, v32, v32
	v_fmac_f32_e32 v103, v34, v34
	v_fmac_f32_e32 v103, v35, v35
	v_fmac_f32_e32 v103, v36, v36
	v_fmac_f32_e32 v103, v37, v37
	v_fmac_f32_e32 v103, v38, v38
	v_fmac_f32_e32 v103, v39, v39
	v_fmac_f32_e32 v103, v40, v40
	v_fmac_f32_e32 v103, v41, v41
	v_fmac_f32_e32 v103, v42, v42
	v_fmac_f32_e32 v103, v43, v43
	v_fmac_f32_e32 v103, v44, v44
	v_fmac_f32_e32 v103, v45, v45
	v_fmac_f32_e32 v103, v46, v46
	v_fmac_f32_e32 v103, v47, v47
	ds_bpermute_b32 v107, v107, v103
	s_and_saveexec_b64 s[8:9], s[6:7]
	s_xor_b64 s[8:9], exec, s[8:9]
	v_mov_b32_e32 v147, s19
	s_andn2_saveexec_b64 s[8:9], s[8:9]
	s_cbranch_execz .Lret_st_e
	v_mov_b32_e32 v147, s19
	v_lshlrev_b64 v[190:191], 8, v[146:147]
	s_waitcnt lgkmcnt(0)
	v_add_f32_e32 v103, v103, v107
	v_lshl_add_u64 v[190:191], s[20:21], 0, v[190:191]
	flat_store_dword v[190:191], v103
	s_branch .Lret_st_e

; __device__ __forceinline__ void ret_mfma(const Params& P, LAS unsigned char* lds, int wave) {
;     ...
;             if (c + 1 < 64) { const size_t r1 = rb + (size_t)(c + 1) * 64;
; #pragma unroll
;                 for (int i = 0; i < 4; ++i) { const int id = t + 512 * i, r = id >> 5, ch = id & 31;
;                     pq[i] = *(const u32x4*)(QK + (r1 + r) * 2048 + hh * 256 + ch * 8); pkk[i] = *(const u32x4*)(QK + (r1 + r) * 2048 + 1024 + hh * 256 + ch * 8); }
;                 pvv = *(const u32x4*)(V + (r1 + vr) * 2048 + hh * 512 + slice * 64 + vc * 8); }
.Lret_s4_e:
	s_waitcnt lgkmcnt(0)
	s_xor_b32 s30, s30, 0x3000
	s_cmp_lt_u32 s14, 62
	s_cbranch_scc0 .Lret_nl_e
	s_lshl_b32 s8, s14, 6
	s_add_i32 s8, s8, 0x80
	s_add_u32 s8, s18, s8
	s_addc_u32 s9, s19, 0
	v_lshl_add_u64 v[32:33], s[8:9], 0, v[92:93]
	v_lshlrev_b64 v[32:33], 12, v[32:33]
	v_lshl_add_u64 v[32:33], v[144:145], 0, v[32:33]
	global_load_dwordx4 v[226:229], v[32:33], off
	global_load_dwordx4 v[230:233], v[32:33], off offset:2048
	v_lshl_add_u64 v[32:33], s[8:9], 0, v[94:95]
	v_lshlrev_b64 v[32:33], 12, v[32:33]
	v_lshl_add_u64 v[32:33], v[144:145], 0, v[32:33]
	global_load_dwordx4 v[234:237], v[32:33], off
	global_load_dwordx4 v[238:241], v[32:33], off offset:2048
	v_lshl_add_u64 v[32:33], s[8:9], 0, v[96:97]
	v_lshlrev_b64 v[32:33], 12, v[32:33]
	v_lshl_add_u64 v[32:33], v[144:145], 0, v[32:33]
	global_load_dwordx4 v[246:249], v[32:33], off
	global_load_dwordx4 v[250:253], v[32:33], off offset:2048
	v_lshl_add_u64 v[32:33], s[8:9], 0, v[98:99]
	v_lshlrev_b64 v[32:33], 12, v[32:33]
	v_lshl_add_u64 v[32:33], v[144:145], 0, v[32:33]
	global_load_dwordx4 v[206:209], v[32:33], off
	global_load_dwordx4 v[130:133], v[32:33], off offset:2048
	v_lshl_add_u64 v[32:33], s[8:9], 0, v[88:89]
	v_lshlrev_b64 v[32:33], 12, v[32:33]
	v_lshl_add_u64 v[32:33], v[124:125], 0, v[32:33]
	global_load_dwordx4 v[134:137], v[32:33], off

; #define LAS __attribute__((address_space(3)))
; __device__ __forceinline__ unsigned cvt_pk_bf16(float lo, float hi) { f32x2 v = {lo, hi}; bf16x2_t b = __builtin_convertvector(v, bf16x2_t); return __builtin_bit_cast(unsigned, b); }
; __device__ __forceinline__ void ret_mfma(const Params& P, LAS unsigned char* lds, int wave) {
;     ...
;             for (int i = 0; i < 4; ++i) { const int id = t + 512 * i, r = id >> 5, ch = id & 31;
;                 *(LAS u32x4*)(lds + Q_OFF + r * QP + ch * 16) = pq[i]; *(LAS u32x4*)(lds + K_OFF + r * QP + ch * 16) = pkk[i]; }
;             *(LAS u32x4*)(lds + V_OFF + vr * VP + vc * 16) = pvv;
;     ...
; #pragma unroll
;                 for (int vb = 0; vb < 2; ++vb)
; #pragma unroll
;                     for (int i = 0; i < 16; ++i) { const int dv = vb * 32 + 8 * (i >> 2) + 4 * hf + (i & 3);
;                         *(LAS bf16_t*)(lds + ST_OFF + dv * QP + (wave * 32 + q32) * 2) = (bf16_t)(cvt_pk_bf16(st[vb][i], 0.f) & 0xffffu); }
;             }
;             if (wave >= 4) {
;                 const int w4 = wave - 4, dvblk = w4 >> 1, nblk = w4 & 1, n = nblk * 32 + q32;
; #pragma unroll
;                 for (int ks = 0; ks < 4; ++ks) {
;                     const LAS unsigned char* p = lds + V_OFF + (16 * ks + trrow) * VP + dvblk * 64 + trcol;
;                     const bf16x8 a = tr_pair(p, p + 4 * VP);
;                     const bf16x8 bs = *(const LAS bf16x8*)(lds + S_OFF + n * SP + (16 * ks + 8 * hf) * 2);
;                     acc = __builtin_amdgcn_mfma_f32_32x32x16_bf16(a, bs, acc, 0, 0, 0);
;                 }
;                 float sq = 0.f;
; #pragma unroll
;                 for (int i = 0; i < 16; ++i) sq += acc[i] * acc[i];
;                 sq += __shfl_xor(sq, 32);
;                 if (hf == 0) rssq[(r0 + n) * 64 + hh * 16 + slice * 2 + dvblk] = sq;
;                 bf16_t* op = V + (r0 + n) * 2048 + hh * 512 + slice * 64 + dvblk * 32 + 4 * hf;
; #pragma unroll
;                 for (int j = 0; j < 4; ++j) { u32x2 w; w.x = cvt_pk_bf16(acc[4 * j], acc[4 * j + 1]); w.y = cvt_pk_bf16(acc[4 * j + 2], acc[4 * j + 3]); *(u32x2*)(op + 8 * j) = w; }
;             }
.Lret_wd_o:
	s_xor_b32 s31, s30, 0x3000
	v_add_u32_e32 v107, s31, v177
	ds_write_b128 v173, v[48:51]
	ds_write_b128 v173, v[52:55] offset:33792
	ds_write_b128 v174, v[56:59]
	ds_write_b128 v174, v[60:63] offset:33792
	ds_write_b128 v175, v[64:67]
	ds_write_b128 v175, v[68:71] offset:33792
	ds_write_b128 v176, v[72:75]
	ds_write_b128 v176, v[76:79] offset:33792
	ds_write_b128 v107, v[80:83]
	s_and_b64 vcc, exec, s[8:9]
	v_cvt_pk_bf16_f32 v218, v0, v1
	v_cvt_pk_bf16_f32 v219, v2, v3
	ds_write_b64 v242, v[218:219]
	v_cvt_pk_bf16_f32 v220, v4, v5
	v_cvt_pk_bf16_f32 v221, v6, v7
	ds_write_b64 v242, v[220:221] offset:16
	v_cvt_pk_bf16_f32 v222, v8, v9
	v_cvt_pk_bf16_f32 v223, v10, v11
	ds_write_b64 v242, v[222:223] offset:32
	v_cvt_pk_bf16_f32 v224, v12, v13
	v_cvt_pk_bf16_f32 v225, v14, v15
	ds_write_b64 v242, v[224:225] offset:48
	v_cvt_pk_bf16_f32 v218, v16, v17
	v_cvt_pk_bf16_f32 v219, v18, v19
	ds_write_b64 v242, v[218:219] offset:16896
	v_cvt_pk_bf16_f32 v220, v20, v21
	v_cvt_pk_bf16_f32 v221, v22, v23
	ds_write_b64 v242, v[220:221] offset:16912
	v_cvt_pk_bf16_f32 v222, v24, v25
	v_cvt_pk_bf16_f32 v223, v26, v27
	ds_write_b64 v242, v[222:223] offset:16928
	v_cvt_pk_bf16_f32 v224, v28, v29
	v_cvt_pk_bf16_f32 v225, v30, v31
	ds_write_b64 v242, v[224:225] offset:16944
	s_cbranch_vccnz .Lret_s4_o
	v_add_u32_e32 v185, s30, v181
	ds_read_b64_tr_b16 v[190:191], v185
	ds_read_b64_tr_b16 v[192:193], v185 offset:768
	v_add_u32_e32 v103, v151, v149
	ds_read_b128 v[194:197], v103
	ds_read_b64_tr_b16 v[198:199], v185 offset:3072
	ds_read_b64_tr_b16 v[200:201], v185 offset:3840
	ds_read_b128 v[202:205], v103 offset:32
	v_and_b32_e32 v107, 64, v184
	v_add_u32_e32 v107, 64, v107
	s_waitcnt lgkmcnt(0)
	v_mfma_f32_32x32x16_bf16 v[32:47], v[190:193], v[194:197], v[32:47]
	s_lshl_b32 s8, s29, 6
	s_or_b32 s8, s18, s8
	v_or_b32_e32 v146, s8, v84
	v_mfma_f32_32x32x16_bf16 v[32:47], v[198:201], v[202:205], v[32:47]
	ds_read_b64_tr_b16 v[190:191], v185 offset:6144
	ds_read_b64_tr_b16 v[192:193], v185 offset:6912
	ds_read_b128 v[194:197], v103 offset:64
	ds_read_b64_tr_b16 v[198:199], v185 offset:9216
	ds_read_b64_tr_b16 v[200:201], v185 offset:9984
	ds_read_b128 v[202:205], v103 offset:96
	v_xor_b32_e32 v103, 32, v184
	v_cmp_lt_i32_e32 vcc, v103, v107
	s_nop 1
	v_cndmask_b32_e32 v107, v184, v103, vcc
	v_lshlrev_b32_e32 v107, 2, v107
	s_waitcnt lgkmcnt(0)
	v_mfma_f32_32x32x16_bf16 v[32:47], v[190:193], v[194:197], v[32:47]
	v_mfma_f32_32x32x16_bf16 v[32:47], v[198:201], v[202:205], v[32:47]
	s_nop 11
	v_mul_f32_e32 v103, v33, v33
	v_fmac_f32_e32 v103, v32, v32
	v_fmac_f32_e32 v103, v34, v34
	v_fmac_f32_e32 v103, v35, v35
	v_fmac_f32_e32 v103, v36, v36
	v_fmac_f32_e32 v103, v37, v37
	v_fmac_f32_e32 v103, v38, v38
	v_fmac_f32_e32 v103, v39, v39
	v_fmac_f32_e32 v103, v40, v40
	v_fmac_f32_e32 v103, v41, v41
	v_fmac_f32_e32 v103, v42, v42
	v_fmac_f32_e32 v103, v43, v43
	v_fmac_f32_e32 v103, v44, v44
	v_fmac_f32_e32 v103, v45, v45
	v_fmac_f32_e32 v103, v46, v46
	v_fmac_f32_e32 v103, v47, v47
	ds_bpermute_b32 v107, v107, v103
	s_and_saveexec_b64 s[8:9], s[6:7]
	s_xor_b64 s[8:9], exec, s[8:9]
	v_mov_b32_e32 v147, s19
	s_andn2_saveexec_b64 s[8:9], s[8:9]
	s_cbranch_execz .Lret_st_o
	v_mov_b32_e32 v147, s19
	v_lshlrev_b64 v[190:191], 8, v[146:147]
	s_waitcnt lgkmcnt(0)
	v_add_f32_e32 v103, v103, v107
	v_lshl_add_u64 v[190:191], s[20:21], 0, v[190:191]
	flat_store_dword v[190:191], v103
	s_branch .Lret_st_o

; #define LAS __attribute__((address_space(3)))
; __device__ __forceinline__ void ret_mfma(const Params& P, LAS unsigned char* lds, int wave) {
;     ...
;         for (int c = 0; c < 64; ++c) {
; #pragma unroll
;             for (int i = 0; i < 4; ++i) { const int id = t + 512 * i, r = id >> 5, ch = id & 31;
;                 *(LAS u32x4*)(lds + Q_OFF + r * QP + ch * 16) = pq[i]; *(LAS u32x4*)(lds + K_OFF + r * QP + ch * 16) = pkk[i]; }
;             *(LAS u32x4*)(lds + V_OFF + vr * VP + vc * 16) = pvv;
;             __syncthreads();
;             if (c + 1 < 64) { const size_t r1 = rb + (size_t)(c + 1) * 64;
; #pragma unroll
;                 for (int i = 0; i < 4; ++i) { const int id = t + 512 * i, r = id >> 5, ch = id & 31;
;                     pq[i] = *(const u32x4*)(QK + (r1 + r) * 2048 + hh * 256 + ch * 8); pkk[i] = *(const u32x4*)(QK + (r1 + r) * 2048 + 1024 + hh * 256 + ch * 8); }
;                 pvv = *(const u32x4*)(V + (r1 + vr) * 2048 + hh * 512 + slice * 64 + vc * 8); }
.Lret_s4_o:
	s_waitcnt lgkmcnt(0)
	s_xor_b32 s30, s30, 0x3000
	s_cmp_lt_u32 s14, 62
	s_cbranch_scc0 .Lret_nl_o
	s_lshl_b32 s8, s14, 6
	s_add_i32 s8, s8, 0x80
	s_add_u32 s8, s18, s8
	s_addc_u32 s9, s19, 0
	v_lshl_add_u64 v[32:33], s[8:9], 0, v[92:93]
	v_lshlrev_b64 v[32:33], 12, v[32:33]
	v_lshl_add_u64 v[32:33], v[144:145], 0, v[32:33]
	global_load_dwordx4 v[48:51], v[32:33], off
	global_load_dwordx4 v[52:55], v[32:33], off offset:2048
	v_lshl_add_u64 v[32:33], s[8:9], 0, v[94:95]
	v_lshlrev_b64 v[32:33], 12, v[32:33]
	v_lshl_add_u64 v[32:33], v[144:145], 0, v[32:33]
	global_load_dwordx4 v[56:59], v[32:33], off
	global_load_dwordx4 v[60:63], v[32:33], off offset:2048
	v_lshl_add_u64 v[32:33], s[8:9], 0, v[96:97]
	v_lshlrev_b64 v[32:33], 12, v[32:33]
	v_lshl_add_u64 v[32:33], v[144:145], 0, v[32:33]
	global_load_dwordx4 v[64:67], v[32:33], off
	global_load_dwordx4 v[68:71], v[32:33], off offset:2048
	v_lshl_add_u64 v[32:33], s[8:9], 0, v[98:99]
	v_lshlrev_b64 v[32:33], 12, v[32:33]
	v_lshl_add_u64 v[32:33], v[144:145], 0, v[32:33]
	global_load_dwordx4 v[72:75], v[32:33], off
	global_load_dwordx4 v[76:79], v[32:33], off offset:2048
	v_lshl_add_u64 v[32:33], s[8:9], 0, v[88:89]
	v_lshlrev_b64 v[32:33], 12, v[32:33]
	v_lshl_add_u64 v[32:33], v[124:125], 0, v[32:33]
	global_load_dwordx4 v[80:83], v[32:33], off
.Lret_nl_o:
	s_cmp_eq_u32 s14, 64
	s_mov_b32 s29, s14
	s_waitcnt lgkmcnt(0)
	s_barrier
	s_cbranch_scc1 .LBB0_248
	s_branch .Lret_even
